# v9 + convert loops: input pointers loaded from kernarg once before the loop instead of per item
# baseline (speedup 1.0000x reference)
; __device__ __forceinline__ void convert_weights(Frame& F, const int part, const int first, const int stride) {
;     bf16* wgla = (bf16*)(F.ws + WS_WGLA); bf16* wswa = (bf16*)(F.ws + WS_WSWA); bf16* wmkv = (bf16*)(F.ws + WS_WMKV);
;     bf16* wout = (bf16*)(F.ws + WS_WOUT); bf16* wup = (bf16*)(F.ws + WS_WUP); bf16* wdn = (bf16*)(F.ws + WS_WDN);
;     constexpr int I_GLA = 32 * 23, I_SWA = 32 * 10, I_MKV = 32 * 4, I_OUT = 32 * 8, I_UP = 32 * 32, I_DN = 128 * 8;
;     const int nl = (part == 2) ? 2 : 1, l0 = part;
;     const int n_gla = (part < 2) ? I_GLA : 0, n_swa = (part > 0) ? I_SWA : 0, n_mkv = (part == 0) ? 4 * I_MKV : 0, n_out = nl * I_OUT, n_up = nl * I_UP, n_dn = nl * I_DN;
;     const int total = n_gla + n_swa + n_mkv + n_out + n_up + n_dn;
;     for (int it = first; it < total; it += stride) {
;         int r = it;
.LBB0_7:
.LBB0_8:
	v_mov_b32_e32 v1, v236
	v_readlane_b32 s15, v254, 0
	s_mov_b64 s[8:9], s[58:59]
	v_readfirstlane_b32 s14, v1
	s_mov_b64 s[0:1], s[78:79]
	s_cmpk_gt_i32 s15, 0xddf
	s_cbranch_scc1 .LBB0_47
	s_add_u32 s16, s0, 0x4300000
	s_addc_u32 s17, s1, 0
	s_add_u32 s18, s0, 0x5300000
	s_addc_u32 s19, s1, 0
	v_ashrrev_i32_e32 v3, 6, v1
	s_add_u32 s20, s0, 0x7300000
	v_lshlrev_b32_e32 v2, 2, v1
	v_lshlrev_b32_e32 v4, 3, v3
	s_addc_u32 s21, s1, 0
	v_and_b32_e32 v40, 0xfc, v2
	v_and_b32_e32 v5, 8, v4
	v_ashrrev_i32_e32 v4, 7, v1
	s_add_u32 s22, s0, 0xf300000
	v_bitop3_b32 v4, v4, v1, 7 bitop3:0x78
	v_lshl_add_u32 v6, v40, 7, 0
	s_addc_u32 s23, s1, 0
	v_lshl_add_u32 v7, v4, 4, v6
	v_lshrrev_b32_e32 v4, 5, v1
	s_add_u32 s24, s0, 0x100000
	v_lshlrev_b32_e32 v42, 2, v3
	v_add_u32_e32 v3, 8, v3
	v_xor_b32_e32 v4, v4, v1
	s_addc_u32 s25, s1, 0
	v_lshrrev_b32_e32 v3, 1, v3
	v_lshlrev_b32_e32 v4, 4, v4
	v_add_u32_e32 v9, 0x200, v1
	v_add_u32_e32 v10, 0x400, v1
	v_add_u32_e32 v11, 0x600, v1
	s_lshl_b32 s4, s15, 4
	v_bitop3_b32 v3, v3, v1, 7 bitop3:0x78
	v_ashrrev_i32_e32 v41, 3, v1
	v_and_b32_e32 v8, 0x70, v4
	v_lshlrev_b32_e32 v4, 3, v1
	v_ashrrev_i32_e32 v50, 3, v9
	v_ashrrev_i32_e32 v51, 3, v10
	v_ashrrev_i32_e32 v52, 3, v11
	s_add_i32 s28, s4, 0xffffd200
	s_lshl_b32 s4, s15, 3
	v_lshl_add_u32 v3, v3, 4, v6
	v_lshl_add_u32 v6, v41, 7, 0
	v_and_b32_e32 v4, 56, v4
	v_lshl_add_u32 v9, v50, 7, 0
	v_lshl_add_u32 v10, v51, 7, 0
	v_lshl_add_u32 v11, v52, 7, 0
	s_add_i32 s30, s4, 0xffffd100
	s_lshl_b32 s4, s15, 1
	v_mov_b32_e32 v2, 0
	s_mov_b32 s5, 0
	v_ashrrev_i32_e32 v43, 31, v42
	s_lshl_b32 s26, s15, 8
	s_lshl_b32 s27, s82, 8
	s_lshl_b32 s29, s82, 4
	s_lshl_b32 s31, s82, 3
	s_add_i32 s33, s4, 0xfffff440
	s_lshl_b32 s34, s82, 1
	s_mov_b32 s35, 0x40000
	s_mov_b32 s36, 0x42000
	s_mov_b32 s37, 0x44000
	s_mov_b32 s38, 0x46000
	v_add_u32_e32 v53, v7, v5
	v_add_u32_e32 v54, v3, v5
	v_add_u32_e32 v55, v6, v8
	v_add_u32_e32 v56, v9, v8
	v_add_u32_e32 v57, v10, v8
	v_add_u32_e32 v58, v11, v8
	s_mov_b32 s39, 0x100000
	s_mov_b32 s40, 0x20000
	s_mov_b32 s41, 0x21000
	s_mov_b32 s42, 0x22000
	s_mov_b32 s43, 0x23000
	s_movk_i32 s44, 0x1610
	s_movk_i32 s45, 0x5840
	v_lshlrev_b32_e32 v44, 2, v40
	v_lshlrev_b32_e32 v46, 1, v4
	s_mov_b32 s46, s15
	v_mov_b64_e32 v[84:85], s[8:9]
	flat_load_dwordx4 v[80:83], v[84:85] offset:24
	flat_load_dwordx2 v[78:79], v[84:85] offset:80
	flat_load_dwordx2 v[76:77], v[84:85] offset:88
	flat_load_dwordx4 v[72:75], v[84:85] offset:96
	flat_load_dwordx2 v[70:71], v[84:85] offset:112
	s_waitcnt vmcnt(0) lgkmcnt(0)
	s_branch .LBB0_12

; #define LAS __attribute__((address_space(3)))
; __device__ __forceinline__ void transpose_item(Frame& F, const float* W, int K, int N, bf16* WT, int kb, int nb, const float* gk = nullptr) {
;     const int l = F.tid & 63, kg = F.tid >> 6, k0 = kb * 64, n0 = nb * 256;
;     const bool inb = (n0 + 4 * l) < N;
;     f32x4 v[2][4];
; #pragma unroll
;     for (int rep = 0; rep < 2; ++rep)
; #pragma unroll
;         for (int kk = 0; kk < 4; ++kk) v[rep][kk] = inb ? *(const f32x4*)(W + (size_t)(k0 + 4 * (kg + 8 * rep) + kk) * N + n0 + 4 * l) : (f32x4){0.f, 0.f, 0.f, 0.f};
;     if (gk) {
; #pragma unroll
;         for (int rep = 0; rep < 2; ++rep) { const f32x4 gg = *(const f32x4*)(gk + k0 + 4 * (kg + 8 * rep)); v[rep][0] = v[rep][0] * gg.x; v[rep][1] = v[rep][1] * gg.y; v[rep][2] = v[rep][2] * gg.z; v[rep][3] = v[rep][3] * gg.w; } }
; #pragma unroll
;     for (int rep = 0; rep < 2; ++rep) { const int kq = kg + 8 * rep;
; #pragma unroll
;         for (int i = 0; i < 4; ++i) { const int n = 4 * l + i; v2u w; w.x = pk2(v[rep][0][i], v[rep][1][i]); w.y = pk2(v[rep][2][i], v[rep][3][i]);
;             *(LAS v2u*)(F.lds + n * 128 + (((kq >> 1) ^ (l & 7)) * 16) + (kq & 1) * 8) = w; } }
;     __syncthreads();
; #pragma unroll
;     for (int q = 0; q < 4; ++q) { const int p = F.tid + 512 * q, n = p >> 3, j = p & 7;
;         const v4u d = *(const LAS v4u*)(F.lds + n * 128 + ((j ^ ((n >> 2) & 7)) * 16));
;         *(v4u*)(WT + (size_t)(n0 + n) * K + k0 + 8 * j) = d; }
;     __syncthreads();
; __device__ __forceinline__ void convert_weights(Frame& F, const int part, const int first, const int stride) {
;     ...
;         if (r < n_up) { const int l = l0 + r / I_UP; r %= I_UP; transpose_item(F, F.in[13] + (size_t)l * D * FF, D, FF, wup + (size_t)l * FF * D, r / 32, r % 32, F.in[12] + l * D); continue; } r -= n_up;
;         { const int l = l0 + r / I_DN; r %= I_DN; transpose_item(F, F.in[14] + (size_t)l * FF * D, FF, D, wdn + (size_t)l * D * FF, r / 8, r % 8); }
.LBB0_12:
	s_cmpk_gt_i32 s46, 0x2df
	s_mov_b64 s[6:7], -1
	s_cbranch_scc0 .LBB0_28
	s_add_i32 s10, s46, 0xfffffd20
	s_cmpk_gt_u32 s10, 0x1ff
	s_cbranch_scc0 .LBB0_25
	s_add_i32 s4, s46, 0xfffffb20
	s_cmpk_gt_u32 s4, 0xff
	s_cbranch_scc0 .LBB0_22
	s_add_i32 s4, s46, 0xfffffa20
	s_cmpk_gt_u32 s4, 0x3ff
	s_cbranch_scc0 .LBB0_17
	v_mov_b64_e32 v[4:5], s[8:9]
	v_mov_b32_e32 v4, v70
	v_mov_b32_e32 v5, v71
	s_add_i32 s4, s46, 0xfffff620
	s_lshr_b32 s4, s4, 10
	s_lshl_b64 s[6:7], s[4:5], 26
	s_lshl_b64 s[12:13], s[4:5], 25
	s_add_u32 s11, s22, s12
	s_addc_u32 s12, s23, s13
	s_and_b32 s13, s30, 0x1fc0
	s_and_b32 s47, s26, 0x700
	v_add_u32_e32 v6, s13, v42
	s_lshl_b32 s4, s47, 2
	v_mov_b32_e32 v45, v2
	v_ashrrev_i32_e32 v7, 31, v6
	v_or_b32_e32 v8, 1, v6
	v_or_b32_e32 v10, 2, v6
	v_or_b32_e32 v12, 3, v6
	v_lshlrev_b64 v[6:7], 13, v[6:7]
	v_ashrrev_i32_e32 v9, 31, v8
	v_ashrrev_i32_e32 v11, 31, v10
	v_ashrrev_i32_e32 v13, 31, v12
	v_lshlrev_b64 v[8:9], 13, v[8:9]
	v_lshlrev_b64 v[10:11], 13, v[10:11]
	v_lshlrev_b64 v[12:13], 13, v[12:13]
	v_add_u32_e32 v36, s47, v41
	v_ashrrev_i32_e32 v37, 31, v36
	v_mov_b32_e32 v47, v2
	v_add_u32_e32 v38, s47, v50
	v_ashrrev_i32_e32 v39, 31, v38
	v_add_u32_e32 v48, s47, v51
	v_ashrrev_i32_e32 v49, 31, v48
	v_add_u32_e32 v60, s47, v52
	v_ashrrev_i32_e32 v61, 31, v60
	s_nop 0
	v_lshl_add_u64 v[4:5], v[4:5], 0, s[6:7]
	v_lshl_add_u64 v[4:5], v[4:5], 0, s[4:5]
	v_lshl_add_u64 v[4:5], v[4:5], 0, v[44:45]
	v_lshl_add_u64 v[20:21], v[4:5], 0, v[6:7]
	v_add_co_u32_e32 v22, vcc, s35, v20
	v_lshl_add_u64 v[8:9], v[4:5], 0, v[8:9]
	s_nop 0
	v_addc_co_u32_e32 v23, vcc, 0, v21, vcc
	v_add_co_u32_e32 v24, vcc, s36, v20
	v_lshl_add_u64 v[14:15], v[4:5], 0, v[10:11]
	s_nop 0
	v_addc_co_u32_e32 v25, vcc, 0, v21, vcc
	v_add_co_u32_e32 v28, vcc, s37, v20
	v_lshl_add_u64 v[16:17], v[4:5], 0, v[12:13]
	s_nop 0
	v_addc_co_u32_e32 v29, vcc, 0, v21, vcc
	v_add_co_u32_e32 v32, vcc, s38, v20
	flat_load_dwordx4 v[4:7], v[20:21]
	s_nop 0
	flat_load_dwordx4 v[8:11], v[8:9]
	s_nop 0
	flat_load_dwordx4 v[12:15], v[14:15]
	s_nop 0
	flat_load_dwordx4 v[16:19], v[16:17]
	v_addc_co_u32_e32 v33, vcc, 0, v21, vcc
	flat_load_dwordx4 v[20:23], v[22:23]
	s_nop 0
	flat_load_dwordx4 v[24:27], v[24:25]
	s_nop 0
	flat_load_dwordx4 v[28:31], v[28:29]
	s_nop 0
	flat_load_dwordx4 v[32:35], v[32:33]
	s_lshl_b32 s4, s13, 1
	s_add_u32 s6, s11, s4
	s_addc_u32 s7, s12, 0
	s_waitcnt vmcnt(0) lgkmcnt(0)
	v_cvt_pk_bf16_f32 v4, v4, v8
	v_cvt_pk_bf16_f32 v8, v5, v9
	v_cvt_pk_bf16_f32 v6, v6, v10
	v_cvt_pk_bf16_f32 v10, v7, v11
	v_cvt_pk_bf16_f32 v5, v12, v16
	v_cvt_pk_bf16_f32 v9, v13, v17
	v_cvt_pk_bf16_f32 v7, v14, v18
	v_cvt_pk_bf16_f32 v11, v15, v19
	ds_write2_b64 v53, v[4:5], v[8:9] offset1:16
	ds_write2_b64 v53, v[6:7], v[10:11] offset0:32 offset1:48
	v_cvt_pk_bf16_f32 v4, v20, v24
	v_cvt_pk_bf16_f32 v5, v28, v32
	v_cvt_pk_bf16_f32 v6, v21, v25
	v_cvt_pk_bf16_f32 v7, v29, v33
	v_cvt_pk_bf16_f32 v8, v22, v26
	v_cvt_pk_bf16_f32 v9, v30, v34
	v_cvt_pk_bf16_f32 v10, v23, v27
	v_cvt_pk_bf16_f32 v11, v31, v35
	ds_write2_b64 v54, v[4:5], v[6:7] offset1:16
	ds_write2_b64 v54, v[8:9], v[10:11] offset0:32 offset1:48
	s_waitcnt lgkmcnt(0)
	s_barrier
	ds_read_b128 v[4:7], v55
	v_lshlrev_b64 v[8:9], 14, v[36:37]
	v_lshl_add_u64 v[8:9], s[6:7], 0, v[8:9]
	v_lshl_add_u64 v[8:9], v[8:9], 0, v[46:47]
	s_waitcnt lgkmcnt(0)
	flat_store_dwordx4 v[8:9], v[4:7]
	ds_read_b128 v[4:7], v56
	v_lshlrev_b64 v[8:9], 14, v[38:39]
	v_lshl_add_u64 v[8:9], s[6:7], 0, v[8:9]
	v_lshl_add_u64 v[8:9], v[8:9], 0, v[46:47]
	s_waitcnt lgkmcnt(0)
	flat_store_dwordx4 v[8:9], v[4:7]
	ds_read_b128 v[4:7], v57
	v_lshlrev_b64 v[8:9], 14, v[48:49]
	v_lshl_add_u64 v[8:9], s[6:7], 0, v[8:9]
	v_lshl_add_u64 v[8:9], v[8:9], 0, v[46:47]
	s_waitcnt lgkmcnt(0)
	flat_store_dwordx4 v[8:9], v[4:7]
	ds_read_b128 v[4:7], v58
	v_lshlrev_b64 v[8:9], 14, v[60:61]
	v_lshl_add_u64 v[8:9], s[6:7], 0, v[8:9]
	v_lshl_add_u64 v[8:9], v[8:9], 0, v[46:47]
	s_mov_b64 s[6:7], 0
	s_waitcnt lgkmcnt(0)
	flat_store_dwordx4 v[8:9], v[4:7]
	s_waitcnt lgkmcnt(0)
	s_barrier
.LBB0_17:
	s_andn2_b64 vcc, exec, s[6:7]
	s_cbranch_vccnz .LBB0_21
	v_mov_b64_e32 v[4:5], s[8:9]
	v_mov_b32_e32 v36, v72
	v_mov_b32_e32 v37, v73
	v_mov_b32_e32 v38, v74
	v_mov_b32_e32 v39, v75
	s_and_b32 s12, s33, 0x7c0
	s_and_b32 s11, s26, 0x1f00
	v_add_u32_e32 v4, s12, v42
	s_lshl_b32 s4, s11, 2
	v_or_b32_e32 v6, 1, v4
	v_mov_b32_e32 v45, v2
	v_ashrrev_i32_e32 v5, 31, v4
	v_or_b32_e32 v8, 2, v4
	v_or_b32_e32 v10, 3, v4
	v_ashrrev_i32_e32 v7, 31, v6
	v_lshlrev_b64 v[4:5], 15, v[4:5]
	v_ashrrev_i32_e32 v9, 31, v8
	v_ashrrev_i32_e32 v11, 31, v10
	v_lshlrev_b64 v[6:7], 15, v[6:7]
	v_lshlrev_b64 v[8:9], 15, v[8:9]
	v_lshlrev_b64 v[10:11], 15, v[10:11]
	s_nop 0
	v_lshl_add_u64 v[12:13], v[38:39], 0, s[4:5]
	v_lshl_add_u64 v[12:13], v[12:13], 0, v[44:45]
	v_lshl_add_u64 v[28:29], v[12:13], 0, v[4:5]
	v_lshl_add_u64 v[4:5], v[12:13], 0, v[6:7]
	v_lshl_add_u64 v[6:7], v[12:13], 0, v[8:9]
	v_lshl_add_u64 v[8:9], v[12:13], 0, v[10:11]
	flat_load_dwordx4 v[12:15], v[28:29]
	flat_load_dwordx4 v[20:23], v[4:5]
	flat_load_dwordx4 v[16:19], v[6:7]
	flat_load_dwordx4 v[24:27], v[8:9]
	v_add_co_u32_e32 v4, vcc, s39, v28
	s_nop 1
	v_addc_co_u32_e32 v5, vcc, 0, v29, vcc
	v_add_co_u32_e32 v8, vcc, 0x108000, v28
	s_nop 1
	v_addc_co_u32_e32 v9, vcc, 0, v29, vcc
	v_add_co_u32_e32 v30, vcc, 0x110000, v28
	flat_load_dwordx4 v[4:7], v[4:5]
	s_nop 0
	flat_load_dwordx4 v[8:11], v[8:9]
	v_addc_co_u32_e32 v31, vcc, 0, v29, vcc
	v_add_co_u32_e32 v32, vcc, 0x118000, v28
	s_nop 1
	v_addc_co_u32_e32 v33, vcc, 0, v29, vcc
	flat_load_dwordx4 v[28:31], v[30:31]
	s_nop 0
	flat_load_dwordx4 v[32:35], v[32:33]
	v_cmp_ne_u64_e32 vcc, 0, v[36:37]
	s_and_saveexec_b64 s[6:7], vcc
	s_cbranch_execz .LBB0_20
	s_lshl_b32 s4, s12, 2
	v_lshl_add_u64 v[36:37], v[36:37], 0, s[4:5]
	v_lshl_add_u64 v[48:49], v[42:43], 2, v[36:37]
	flat_load_dwordx4 v[36:39], v[48:49]
	flat_load_dwordx4 v[60:63], v[48:49] offset:128
	s_waitcnt vmcnt(0) lgkmcnt(0)
	v_pk_mul_f32 v[14:15], v[14:15], v[36:37] op_sel_hi:[1,0]
	v_pk_mul_f32 v[12:13], v[12:13], v[36:37] op_sel_hi:[1,0]
	v_pk_mul_f32 v[22:23], v[22:23], v[36:37] op_sel:[0,1]
	v_pk_mul_f32 v[20:21], v[20:21], v[36:37] op_sel:[0,1]
	v_pk_mul_f32 v[18:19], v[18:19], v[38:39] op_sel_hi:[1,0]
	v_pk_mul_f32 v[16:17], v[16:17], v[38:39] op_sel_hi:[1,0]
	v_mov_b32_e32 v36, v39
	v_mov_b32_e32 v38, v63
	v_pk_mul_f32 v[6:7], v[6:7], v[60:61] op_sel_hi:[1,0]
	v_pk_mul_f32 v[4:5], v[4:5], v[60:61] op_sel_hi:[1,0]
	v_pk_mul_f32 v[10:11], v[10:11], v[60:61] op_sel:[0,1]
	v_pk_mul_f32 v[8:9], v[8:9], v[60:61] op_sel:[0,1]
	v_pk_mul_f32 v[30:31], v[30:31], v[62:63] op_sel_hi:[1,0]
	v_pk_mul_f32 v[28:29], v[28:29], v[62:63] op_sel_hi:[1,0]
	v_pk_mul_f32 v[26:27], v[26:27], v[36:37] op_sel_hi:[1,0]
	v_pk_mul_f32 v[24:25], v[24:25], v[36:37] op_sel_hi:[1,0]
	v_pk_mul_f32 v[34:35], v[34:35], v[38:39] op_sel_hi:[1,0]
	v_pk_mul_f32 v[32:33], v[32:33], v[38:39] op_sel_hi:[1,0]

; #define LAS __attribute__((address_space(3)))
; __device__ __forceinline__ void transpose_item(Frame& F, const float* W, int K, int N, bf16* WT, int kb, int nb, const float* gk = nullptr) {
;     const int l = F.tid & 63, kg = F.tid >> 6, k0 = kb * 64, n0 = nb * 256;
;     const bool inb = (n0 + 4 * l) < N;
;     f32x4 v[2][4];
; #pragma unroll
;     for (int rep = 0; rep < 2; ++rep)
; #pragma unroll
;         for (int kk = 0; kk < 4; ++kk) v[rep][kk] = inb ? *(const f32x4*)(W + (size_t)(k0 + 4 * (kg + 8 * rep) + kk) * N + n0 + 4 * l) : (f32x4){0.f, 0.f, 0.f, 0.f};
;     if (gk) {
; #pragma unroll
;         for (int rep = 0; rep < 2; ++rep) { const f32x4 gg = *(const f32x4*)(gk + k0 + 4 * (kg + 8 * rep)); v[rep][0] = v[rep][0] * gg.x; v[rep][1] = v[rep][1] * gg.y; v[rep][2] = v[rep][2] * gg.z; v[rep][3] = v[rep][3] * gg.w; } }
; #pragma unroll
;     for (int rep = 0; rep < 2; ++rep) { const int kq = kg + 8 * rep;
; #pragma unroll
;         for (int i = 0; i < 4; ++i) { const int n = 4 * l + i; v2u w; w.x = pk2(v[rep][0][i], v[rep][1][i]); w.y = pk2(v[rep][2][i], v[rep][3][i]);
;             *(LAS v2u*)(F.lds + n * 128 + (((kq >> 1) ^ (l & 7)) * 16) + (kq & 1) * 8) = w; } }
;     __syncthreads();
; #pragma unroll
;     for (int q = 0; q < 4; ++q) { const int p = F.tid + 512 * q, n = p >> 3, j = p & 7;
;         const v4u d = *(const LAS v4u*)(F.lds + n * 128 + ((j ^ ((n >> 2) & 7)) * 16));
;         *(v4u*)(WT + (size_t)(n0 + n) * K + k0 + 8 * j) = d; }
;     __syncthreads();
; __device__ __forceinline__ void convert_weights(Frame& F, const int part, const int first, const int stride) {
;     ...
;         if (r < n_out) { const int l = l0 + r / I_OUT; r %= I_OUT; transpose_item(F, F.in[11] + (size_t)l * D * D, D, D, wout + (size_t)l * D * D, r / 8, r % 8); continue; } r -= n_out;
.LBB0_22:
	s_andn2_b64 vcc, exec, s[6:7]
	s_cbranch_vccnz .LBB0_24
	v_mov_b64_e32 v[4:5], s[8:9]
	v_mov_b32_e32 v4, v76
	v_mov_b32_e32 v5, v77
	s_add_i32 s4, s30, 0x800
	s_and_b32 s6, s26, 0x700
	s_and_b32 s7, s4, 0x7c0
	s_lshl_b32 s4, s6, 2
	v_add_u32_e32 v6, s7, v42
	v_mov_b32_e32 v45, v2
	v_ashrrev_i32_e32 v7, 31, v6
	v_or_b32_e32 v8, 1, v6
	v_or_b32_e32 v10, 2, v6
	v_or_b32_e32 v12, 3, v6
	v_lshlrev_b64 v[6:7], 13, v[6:7]
	v_ashrrev_i32_e32 v9, 31, v8
	v_ashrrev_i32_e32 v11, 31, v10
	v_ashrrev_i32_e32 v13, 31, v12
	v_lshlrev_b64 v[8:9], 13, v[8:9]
	v_lshlrev_b64 v[10:11], 13, v[10:11]
	v_lshlrev_b64 v[12:13], 13, v[12:13]
	v_add_u32_e32 v36, s6, v41
	v_add_u32_e32 v38, s6, v50
	v_add_u32_e32 v48, s6, v51
	v_add_u32_e32 v60, s6, v52
	v_ashrrev_i32_e32 v37, 31, v36
	v_mov_b32_e32 v47, v2
	v_ashrrev_i32_e32 v39, 31, v38
	v_ashrrev_i32_e32 v49, 31, v48
	v_ashrrev_i32_e32 v61, 31, v60
	s_nop 0
	v_lshl_add_u64 v[4:5], v[4:5], 0, s[4:5]
	v_lshl_add_u64 v[4:5], v[4:5], 0, v[44:45]
	v_lshl_add_u64 v[20:21], v[4:5], 0, v[6:7]
	v_add_co_u32_e32 v22, vcc, s35, v20
	v_lshl_add_u64 v[8:9], v[4:5], 0, v[8:9]
	s_nop 0
	v_addc_co_u32_e32 v23, vcc, 0, v21, vcc
	v_add_co_u32_e32 v24, vcc, s36, v20
	v_lshl_add_u64 v[14:15], v[4:5], 0, v[10:11]
	s_nop 0
	v_addc_co_u32_e32 v25, vcc, 0, v21, vcc
	v_add_co_u32_e32 v28, vcc, s37, v20
	v_lshl_add_u64 v[16:17], v[4:5], 0, v[12:13]
	s_nop 0
	v_addc_co_u32_e32 v29, vcc, 0, v21, vcc
	v_add_co_u32_e32 v32, vcc, s38, v20
	flat_load_dwordx4 v[4:7], v[20:21]
	s_nop 0
	flat_load_dwordx4 v[8:11], v[8:9]
	s_nop 0
	flat_load_dwordx4 v[12:15], v[14:15]
	s_nop 0
	flat_load_dwordx4 v[16:19], v[16:17]
	v_addc_co_u32_e32 v33, vcc, 0, v21, vcc
	flat_load_dwordx4 v[20:23], v[22:23]
	s_nop 0
	flat_load_dwordx4 v[24:27], v[24:25]
	s_nop 0
	flat_load_dwordx4 v[28:31], v[28:29]
	s_nop 0
	flat_load_dwordx4 v[32:35], v[32:33]
	s_lshl_b32 s4, s7, 1
	s_add_u32 s6, s18, s4
	s_addc_u32 s7, s19, 0
	s_waitcnt vmcnt(0) lgkmcnt(0)
	v_cvt_pk_bf16_f32 v4, v4, v8
	v_cvt_pk_bf16_f32 v8, v5, v9
	v_cvt_pk_bf16_f32 v6, v6, v10
	v_cvt_pk_bf16_f32 v10, v7, v11
	v_cvt_pk_bf16_f32 v5, v12, v16
	v_cvt_pk_bf16_f32 v9, v13, v17
	v_cvt_pk_bf16_f32 v7, v14, v18
	v_cvt_pk_bf16_f32 v11, v15, v19
	ds_write2_b64 v53, v[4:5], v[8:9] offset1:16
	ds_write2_b64 v53, v[6:7], v[10:11] offset0:32 offset1:48
	v_cvt_pk_bf16_f32 v4, v20, v24
	v_cvt_pk_bf16_f32 v5, v28, v32
	v_cvt_pk_bf16_f32 v6, v21, v25
	v_cvt_pk_bf16_f32 v7, v29, v33
	v_cvt_pk_bf16_f32 v8, v22, v26
	v_cvt_pk_bf16_f32 v9, v30, v34
	v_cvt_pk_bf16_f32 v10, v23, v27
	v_cvt_pk_bf16_f32 v11, v31, v35
	ds_write2_b64 v54, v[4:5], v[6:7] offset1:16
	ds_write2_b64 v54, v[8:9], v[10:11] offset0:32 offset1:48
	s_waitcnt lgkmcnt(0)
	s_barrier
	ds_read_b128 v[4:7], v55
	v_lshlrev_b64 v[8:9], 12, v[36:37]
	v_lshl_add_u64 v[8:9], s[6:7], 0, v[8:9]
	v_lshl_add_u64 v[8:9], v[8:9], 0, v[46:47]
	s_waitcnt lgkmcnt(0)
	flat_store_dwordx4 v[8:9], v[4:7]
	ds_read_b128 v[4:7], v56
	v_lshlrev_b64 v[8:9], 12, v[38:39]
	v_lshl_add_u64 v[8:9], s[6:7], 0, v[8:9]
	v_lshl_add_u64 v[8:9], v[8:9], 0, v[46:47]
	s_waitcnt lgkmcnt(0)
	flat_store_dwordx4 v[8:9], v[4:7]
	ds_read_b128 v[4:7], v57
	v_lshlrev_b64 v[8:9], 12, v[48:49]
	v_lshl_add_u64 v[8:9], s[6:7], 0, v[8:9]
	v_lshl_add_u64 v[8:9], v[8:9], 0, v[46:47]
	s_waitcnt lgkmcnt(0)
	flat_store_dwordx4 v[8:9], v[4:7]
	ds_read_b128 v[4:7], v58
	v_lshlrev_b64 v[8:9], 12, v[60:61]
	v_lshl_add_u64 v[8:9], s[6:7], 0, v[8:9]
	v_lshl_add_u64 v[8:9], v[8:9], 0, v[46:47]
	s_waitcnt lgkmcnt(0)
	flat_store_dwordx4 v[8:9], v[4:7]
	s_waitcnt lgkmcnt(0)
	s_barrier

; #define LAS __attribute__((address_space(3)))
; __device__ __forceinline__ void transpose_item(Frame& F, const float* W, int K, int N, bf16* WT, int kb, int nb, const float* gk = nullptr) {
;     const int l = F.tid & 63, kg = F.tid >> 6, k0 = kb * 64, n0 = nb * 256;
;     const bool inb = (n0 + 4 * l) < N;
;     f32x4 v[2][4];
; #pragma unroll
;     for (int rep = 0; rep < 2; ++rep)
; #pragma unroll
;         for (int kk = 0; kk < 4; ++kk) v[rep][kk] = inb ? *(const f32x4*)(W + (size_t)(k0 + 4 * (kg + 8 * rep) + kk) * N + n0 + 4 * l) : (f32x4){0.f, 0.f, 0.f, 0.f};
;     if (gk) {
; #pragma unroll
;         for (int rep = 0; rep < 2; ++rep) { const f32x4 gg = *(const f32x4*)(gk + k0 + 4 * (kg + 8 * rep)); v[rep][0] = v[rep][0] * gg.x; v[rep][1] = v[rep][1] * gg.y; v[rep][2] = v[rep][2] * gg.z; v[rep][3] = v[rep][3] * gg.w; } }
; #pragma unroll
;     for (int rep = 0; rep < 2; ++rep) { const int kq = kg + 8 * rep;
; #pragma unroll
;         for (int i = 0; i < 4; ++i) { const int n = 4 * l + i; v2u w; w.x = pk2(v[rep][0][i], v[rep][1][i]); w.y = pk2(v[rep][2][i], v[rep][3][i]);
;             *(LAS v2u*)(F.lds + n * 128 + (((kq >> 1) ^ (l & 7)) * 16) + (kq & 1) * 8) = w; } }
;     __syncthreads();
; #pragma unroll
;     for (int q = 0; q < 4; ++q) { const int p = F.tid + 512 * q, n = p >> 3, j = p & 7;
;         const v4u d = *(const LAS v4u*)(F.lds + n * 128 + ((j ^ ((n >> 2) & 7)) * 16));
;         *(v4u*)(WT + (size_t)(n0 + n) * K + k0 + 8 * j) = d; }
;     __syncthreads();
; __device__ __forceinline__ void convert_weights(Frame& F, const int part, const int first, const int stride) {
;     ...
;         if (r < n_mkv) { const int l = r / I_MKV; r -= l * I_MKV; transpose_item(F, F.in[10] + (size_t)l * D * 1024, D, 1024, wmkv + (size_t)l * 1024 * D, r / 4, r % 4); continue; } r -= n_mkv;
.LBB0_25:
	s_andn2_b64 vcc, exec, s[6:7]
	s_cbranch_vccnz .LBB0_27
	v_mov_b64_e32 v[4:5], s[8:9]
	v_mov_b32_e32 v4, v78
	v_mov_b32_e32 v5, v79
	s_lshr_b32 s4, s10, 7
	s_lshl_b64 s[6:7], s[4:5], 23
	s_lshl_b64 s[10:11], s[4:5], 22
	s_add_u32 s10, s16, s10
	s_addc_u32 s11, s17, s11
	s_and_b32 s12, s28, 0x7c0
	s_and_b32 s13, s26, 0x300
	v_add_u32_e32 v6, s12, v42
	s_lshl_b32 s4, s13, 2
	v_mov_b32_e32 v45, v2
	v_ashrrev_i32_e32 v7, 31, v6
	v_or_b32_e32 v8, 1, v6
	v_or_b32_e32 v10, 2, v6
	v_or_b32_e32 v12, 3, v6
	v_lshlrev_b64 v[6:7], 12, v[6:7]
	v_ashrrev_i32_e32 v9, 31, v8
	v_ashrrev_i32_e32 v11, 31, v10
	v_ashrrev_i32_e32 v13, 31, v12
	v_lshlrev_b64 v[8:9], 12, v[8:9]
	v_lshlrev_b64 v[10:11], 12, v[10:11]
	v_lshlrev_b64 v[12:13], 12, v[12:13]
	v_add_u32_e32 v36, s13, v41
	v_ashrrev_i32_e32 v37, 31, v36
	v_mov_b32_e32 v47, v2
	v_add_u32_e32 v38, s13, v50
	v_ashrrev_i32_e32 v39, 31, v38
	v_add_u32_e32 v48, s13, v51
	v_ashrrev_i32_e32 v49, 31, v48
	v_add_u32_e32 v60, s13, v52
	v_ashrrev_i32_e32 v61, 31, v60
	s_nop 0
	v_lshl_add_u64 v[4:5], v[4:5], 0, s[6:7]
	v_lshl_add_u64 v[4:5], v[4:5], 0, s[4:5]
	v_lshl_add_u64 v[4:5], v[4:5], 0, v[44:45]
	v_lshl_add_u64 v[20:21], v[4:5], 0, v[6:7]
	v_add_co_u32_e32 v22, vcc, s40, v20
	v_lshl_add_u64 v[8:9], v[4:5], 0, v[8:9]
	s_nop 0
	v_addc_co_u32_e32 v23, vcc, 0, v21, vcc
	v_add_co_u32_e32 v24, vcc, s41, v20
	v_lshl_add_u64 v[14:15], v[4:5], 0, v[10:11]
	s_nop 0
	v_addc_co_u32_e32 v25, vcc, 0, v21, vcc
	v_add_co_u32_e32 v28, vcc, s42, v20
	v_lshl_add_u64 v[16:17], v[4:5], 0, v[12:13]
	s_nop 0
	v_addc_co_u32_e32 v29, vcc, 0, v21, vcc
	v_add_co_u32_e32 v32, vcc, s43, v20
	flat_load_dwordx4 v[4:7], v[20:21]
	s_nop 0
	flat_load_dwordx4 v[8:11], v[8:9]
	s_nop 0
	flat_load_dwordx4 v[12:15], v[14:15]
	s_nop 0
	flat_load_dwordx4 v[16:19], v[16:17]
	v_addc_co_u32_e32 v33, vcc, 0, v21, vcc
	flat_load_dwordx4 v[20:23], v[22:23]
	s_nop 0
	flat_load_dwordx4 v[24:27], v[24:25]
	s_nop 0
	flat_load_dwordx4 v[28:31], v[28:29]
	s_nop 0
	flat_load_dwordx4 v[32:35], v[32:33]
	s_lshl_b32 s4, s12, 1
	s_add_u32 s6, s10, s4
	s_addc_u32 s7, s11, 0
	s_waitcnt vmcnt(0) lgkmcnt(0)
	v_cvt_pk_bf16_f32 v4, v4, v8
	v_cvt_pk_bf16_f32 v8, v5, v9
	v_cvt_pk_bf16_f32 v6, v6, v10
	v_cvt_pk_bf16_f32 v10, v7, v11
	v_cvt_pk_bf16_f32 v5, v12, v16
	v_cvt_pk_bf16_f32 v9, v13, v17
	v_cvt_pk_bf16_f32 v7, v14, v18
	v_cvt_pk_bf16_f32 v11, v15, v19
	ds_write2_b64 v53, v[4:5], v[8:9] offset1:16
	ds_write2_b64 v53, v[6:7], v[10:11] offset0:32 offset1:48
	v_cvt_pk_bf16_f32 v4, v20, v24
	v_cvt_pk_bf16_f32 v5, v28, v32
	v_cvt_pk_bf16_f32 v6, v21, v25
	v_cvt_pk_bf16_f32 v7, v29, v33
	v_cvt_pk_bf16_f32 v8, v22, v26
	v_cvt_pk_bf16_f32 v9, v30, v34
	v_cvt_pk_bf16_f32 v10, v23, v27
	v_cvt_pk_bf16_f32 v11, v31, v35
	ds_write2_b64 v54, v[4:5], v[6:7] offset1:16
	ds_write2_b64 v54, v[8:9], v[10:11] offset0:32 offset1:48
	s_waitcnt lgkmcnt(0)
	s_barrier
	ds_read_b128 v[4:7], v55
	v_lshlrev_b64 v[8:9], 12, v[36:37]
	v_lshl_add_u64 v[8:9], s[6:7], 0, v[8:9]
	v_lshl_add_u64 v[8:9], v[8:9], 0, v[46:47]
	s_waitcnt lgkmcnt(0)
	flat_store_dwordx4 v[8:9], v[4:7]
	ds_read_b128 v[4:7], v56
	v_lshlrev_b64 v[8:9], 12, v[38:39]
	v_lshl_add_u64 v[8:9], s[6:7], 0, v[8:9]
	v_lshl_add_u64 v[8:9], v[8:9], 0, v[46:47]
	s_waitcnt lgkmcnt(0)
	flat_store_dwordx4 v[8:9], v[4:7]
	ds_read_b128 v[4:7], v57
	v_lshlrev_b64 v[8:9], 12, v[48:49]
	v_lshl_add_u64 v[8:9], s[6:7], 0, v[8:9]
	v_lshl_add_u64 v[8:9], v[8:9], 0, v[46:47]
	s_waitcnt lgkmcnt(0)
	flat_store_dwordx4 v[8:9], v[4:7]
	ds_read_b128 v[4:7], v58
	v_lshlrev_b64 v[8:9], 12, v[60:61]
	v_lshl_add_u64 v[8:9], s[6:7], 0, v[8:9]
	v_lshl_add_u64 v[8:9], v[8:9], 0, v[46:47]
	s_waitcnt lgkmcnt(0)
	flat_store_dwordx4 v[8:9], v[4:7]
	s_waitcnt lgkmcnt(0)
	s_barrier

; __device__ __forceinline__ void transpose_item(Frame& F, const float* W, int K, int N, bf16* WT, int kb, int nb, const float* gk = nullptr) {
;     const int l = F.tid & 63, kg = F.tid >> 6, k0 = kb * 64, n0 = nb * 256;
;     const bool inb = (n0 + 4 * l) < N;
;     f32x4 v[2][4];
; #pragma unroll
;     for (int rep = 0; rep < 2; ++rep)
; #pragma unroll
;         for (int kk = 0; kk < 4; ++kk) v[rep][kk] = inb ? *(const f32x4*)(W + (size_t)(k0 + 4 * (kg + 8 * rep) + kk) * N + n0 + 4 * l) : (f32x4){0.f, 0.f, 0.f, 0.f};
; __device__ __forceinline__ void convert_weights(Frame& F, const int part, const int first, const int stride) {
;     ...
;         if (r < n_gla) { const int l = part; transpose_item(F, F.in[4] + (size_t)l * D * GLA_IN, D, GLA_IN, wgla + (size_t)l * GLA_NP * D, r / 23, r % 23, F.in[3] + (2 * l) * D); continue; } r -= n_gla;
.LBB0_28:
	s_andn2_b64 vcc, exec, s[6:7]
	s_cbranch_vccnz .LBB0_11
	v_mov_b64_e32 v[4:5], s[8:9]
	v_mov_b32_e32 v34, v80
	v_mov_b32_e32 v35, v81
	v_mov_b32_e32 v36, v82
	v_mov_b32_e32 v37, v83
	s_mul_hi_i32 s4, s46, 0xb21642c9
	s_add_i32 s4, s4, s46
	s_lshr_b32 s6, s4, 31
	s_ashr_i32 s4, s4, 4
	s_add_i32 s4, s4, s6
	s_lshl_b32 s10, s4, 6
	s_mulk_i32 s4, 0xe900
	s_add_i32 s6, s26, s4
	v_mov_b32_e32 v8, v2
	v_mov_b32_e32 v9, v2
	s_ashr_i32 s7, s6, 31
	v_mov_b32_e32 v45, v2
	v_mov_b32_e32 v6, v2
	v_mov_b32_e32 v7, v2
	v_add_u32_e32 v3, s6, v40
	v_mov_b64_e32 v[12:13], v[8:9]
	v_add_u32_e32 v47, s10, v42
	v_cmp_gt_i32_e32 vcc, s44, v3
	v_mov_b64_e32 v[10:11], v[6:7]
	s_nop 0
	v_lshl_add_u64 v[4:5], s[6:7], 2, v[36:37]
	v_lshl_add_u64 v[48:49], v[4:5], 0, v[44:45]
	s_and_saveexec_b64 s[12:13], vcc
	s_cbranch_execz .LBB0_31
	v_mad_i64_i32 v[4:5], s[48:49], v47, s45, v[48:49]
	flat_load_dwordx4 v[10:13], v[4:5]

; __device__ __forceinline__ void convert_weights(Frame& F, const int part, const int first, const int stride) {
;     bf16* wgla = (bf16*)(F.ws + WS_WGLA); bf16* wswa = (bf16*)(F.ws + WS_WSWA); bf16* wmkv = (bf16*)(F.ws + WS_WMKV);
;     bf16* wout = (bf16*)(F.ws + WS_WOUT); bf16* wup = (bf16*)(F.ws + WS_WUP); bf16* wdn = (bf16*)(F.ws + WS_WDN);
;     constexpr int I_GLA = 32 * 23, I_SWA = 32 * 10, I_MKV = 32 * 4, I_OUT = 32 * 8, I_UP = 32 * 32, I_DN = 128 * 8;
;     const int nl = (part == 2) ? 2 : 1, l0 = part;
;     const int n_gla = (part < 2) ? I_GLA : 0, n_swa = (part > 0) ? I_SWA : 0, n_mkv = (part == 0) ? 4 * I_MKV : 0, n_out = nl * I_OUT, n_up = nl * I_UP, n_dn = nl * I_DN;
;     const int total = n_gla + n_swa + n_mkv + n_out + n_up + n_dn;
;     for (int it = first; it < total; it += stride) {
.LBB0_632:
	s_add_i32 s9, s7, 1
	s_cmp_eq_u32 s9, 2
	s_cselect_b32 s12, 2, 1
	s_cmp_lt_u32 s33, 2
	s_cselect_b32 s10, 0x2e0, 0
	s_lshl_b32 s11, s12, 8
	s_add_i32 s0, s10, s11
	s_lshl_b32 s13, s12, 11
	s_or_b32 s52, s0, s13
	s_addk_i32 s52, 0x140
	s_cmp_ge_i32 s8, s52
	s_cbranch_scc1 .LBB0_705
	s_add_u32 s53, s42, 0x5300000
	s_addc_u32 s57, s43, 0
	s_add_u32 s58, s42, 0x7300000
	s_addc_u32 s59, s43, 0
	s_add_u32 s60, s42, 0xf300000
	s_addc_u32 s61, s43, 0
	s_lshl_b32 s62, s12, 10
	s_mul_i32 s5, s7, 0xa00000
	s_mul_hi_u32 s4, s7, 0xa00000
	s_add_u32 s5, s42, s5
	s_addc_u32 s4, s43, s4
	v_ashrrev_i32_e32 v0, 6, v163
	s_waitcnt lgkmcnt(0)
	v_lshlrev_b32_e32 v1, 2, v163
	s_add_u32 s63, s5, 0x2f00000
	v_and_b32_e32 v36, 0xfc, v1
	v_lshlrev_b32_e32 v38, 2, v0
	v_lshlrev_b32_e32 v1, 3, v0
	v_add_u32_e32 v0, 8, v0
	s_addc_u32 s64, s4, 0
	s_lshl_b32 s4, s7, 12
	s_mul_i32 s15, s9, 0x1700000
	v_lshrrev_b32_e32 v0, 1, v0
	s_mul_hi_u32 s14, s9, 0x1700000
	s_add_u32 s15, s42, s15
	v_lshl_add_u32 v2, v36, 7, 0
	v_bitop3_b32 v0, v0, v163, 7 bitop3:0x78
	s_addc_u32 s14, s43, s14
	v_lshl_add_u32 v44, v0, 4, v2
	v_lshrrev_b32_e32 v0, 5, v163
	s_add_u32 s65, s15, 0x100000
	v_xor_b32_e32 v0, v0, v163
	s_addc_u32 s66, s14, 0
	v_and_b32_e32 v37, 8, v1
	v_ashrrev_i32_e32 v1, 7, v163
	v_lshlrev_b32_e32 v0, 4, v0
	s_sub_i32 s14, 0xfffffec0, s10
	s_mulk_i32 s12, 0x500
	v_bitop3_b32 v1, v1, v163, 7 bitop3:0x78
	v_ashrrev_i32_e32 v45, 3, v163
	v_and_b32_e32 v47, 0x70, v0
	v_lshlrev_b32_e32 v0, 3, v163
	v_ashrrev_i32_e32 v48, 3, v157
	v_ashrrev_i32_e32 v50, 3, v156
	v_ashrrev_i32_e32 v52, 3, v97
	v_readlane_b32 s15, v254, 59
	s_sub_i32 s71, s14, s12
	s_sub_i32 s72, 0xfffff600, s13
	s_lshl_b32 s12, s8, 3
	s_lshl_b32 s13, s10, 3
	s_mul_hi_u32 s1, s7, 0x1300000
	s_mul_i32 s0, s7, 0x1300000
	s_mov_b32 s5, s27
	s_mul_hi_u32 s47, s9, 0x2c20000
	s_mul_i32 s46, s9, 0x2c20000
	s_lshl_b32 s48, s9, 12
	s_mov_b32 s49, s27
	v_lshl_add_u32 v41, v1, 4, v2
	v_lshl_add_u32 v46, v45, 7, 0
	v_and_b32_e32 v40, 56, v0
	v_lshl_add_u32 v49, v48, 7, 0
	v_lshl_add_u32 v51, v50, 7, 0
	v_lshl_add_u32 v53, v52, 7, 0
	v_ashrrev_i32_e32 v39, 31, v38
	s_lshl_b32 s67, s8, 8
	s_lshl_b32 s68, s15, 8
	s_sub_i32 s69, 0, s10
	s_sub_i32 s70, s14, s11
	s_sub_i32 s73, s12, s13
	s_lshl_b32 s84, s15, 3
	v_mov_b64_e32 v[76:77], s[44:45]
	flat_load_dwordx4 v[72:75], v[76:77] offset:24
	flat_load_dwordx2 v[70:71], v[76:77] offset:64
	flat_load_dwordx2 v[68:69], v[76:77] offset:88
	flat_load_dwordx4 v[64:67], v[76:77] offset:96
	flat_load_dwordx2 v[62:63], v[76:77] offset:112
	s_waitcnt vmcnt(0) lgkmcnt(0)
	s_branch .LBB0_636

; #define LAS __attribute__((address_space(3)))
; __device__ __forceinline__ void transpose_item(Frame& F, const float* W, int K, int N, bf16* WT, int kb, int nb, const float* gk = nullptr) {
;     const int l = F.tid & 63, kg = F.tid >> 6, k0 = kb * 64, n0 = nb * 256;
;     const bool inb = (n0 + 4 * l) < N;
;     f32x4 v[2][4];
; #pragma unroll
;     for (int rep = 0; rep < 2; ++rep)
; #pragma unroll
;         for (int kk = 0; kk < 4; ++kk) v[rep][kk] = inb ? *(const f32x4*)(W + (size_t)(k0 + 4 * (kg + 8 * rep) + kk) * N + n0 + 4 * l) : (f32x4){0.f, 0.f, 0.f, 0.f};
;     if (gk) {
; #pragma unroll
;         for (int rep = 0; rep < 2; ++rep) { const f32x4 gg = *(const f32x4*)(gk + k0 + 4 * (kg + 8 * rep)); v[rep][0] = v[rep][0] * gg.x; v[rep][1] = v[rep][1] * gg.y; v[rep][2] = v[rep][2] * gg.z; v[rep][3] = v[rep][3] * gg.w; } }
; #pragma unroll
;     for (int rep = 0; rep < 2; ++rep) { const int kq = kg + 8 * rep;
; #pragma unroll
;         for (int i = 0; i < 4; ++i) { const int n = 4 * l + i; v2u w; w.x = pk2(v[rep][0][i], v[rep][1][i]); w.y = pk2(v[rep][2][i], v[rep][3][i]);
;             *(LAS v2u*)(F.lds + n * 128 + (((kq >> 1) ^ (l & 7)) * 16) + (kq & 1) * 8) = w; } }
;     __syncthreads();
; #pragma unroll
;     for (int q = 0; q < 4; ++q) { const int p = F.tid + 512 * q, n = p >> 3, j = p & 7;
;         const v4u d = *(const LAS v4u*)(F.lds + n * 128 + ((j ^ ((n >> 2) & 7)) * 16));
;         *(v4u*)(WT + (size_t)(n0 + n) * K + k0 + 8 * j) = d; }
;     __syncthreads();
; __device__ __forceinline__ void convert_weights(Frame& F, const int part, const int first, const int stride) {
;     ...
;         if (r < n_up) { const int l = l0 + r / I_UP; r %= I_UP; transpose_item(F, F.in[13] + (size_t)l * D * FF, D, FF, wup + (size_t)l * FF * D, r / 32, r % 32, F.in[12] + l * D); continue; } r -= n_up;
;         { const int l = l0 + r / I_DN; r %= I_DN; transpose_item(F, F.in[14] + (size_t)l * FF * D, FF, D, wdn + (size_t)l * D * FF, r / 8, r % 8); }
.LBB0_636:
	s_cmp_ge_i32 s8, s10
	s_mov_b64 s[14:15], -1
	s_cbranch_scc0 .LBB0_686
	s_add_i32 s85, s69, s8
	s_cmpk_gt_i32 s85, 0x13f
	s_cbranch_scc0 .LBB0_665
	s_add_i32 s92, s85, 0xfffffec0
	s_cmp_ge_i32 s92, s11
	s_cbranch_scc0 .LBB0_662
	s_add_i32 s18, s70, s8
	s_cmp_ge_i32 s18, s62
	s_cbranch_scc0 .LBB0_641
	v_mov_b64_e32 v[0:1], s[44:45]
	v_mov_b32_e32 v0, v62
	v_mov_b32_e32 v1, v63
	s_add_i32 s12, s71, s8
	s_lshr_b32 s12, s12, 10
	s_add_i32 s26, s12, s9
	s_lshl_b64 s[12:13], s[26:27], 26
	v_lshlrev_b32_e32 v2, 2, v36
	v_mov_b32_e32 v3, v96
	s_nop 0
	v_lshl_add_u64 v[0:1], v[0:1], 0, s[12:13]
	s_lshl_b64 s[12:13], s[26:27], 25
	s_add_u32 s14, s60, s12
	s_addc_u32 s15, s61, s13
	s_add_i32 s12, s72, s73
	s_and_b32 s40, s12, 0x1fc0
	s_and_b32 s19, s67, 0x700
	v_add_u32_e32 v12, s40, v38
	s_lshl_b32 s26, s19, 2
	v_lshl_add_u64 v[0:1], v[0:1], 0, s[26:27]
	v_ashrrev_i32_e32 v13, 31, v12
	v_lshl_add_u64 v[14:15], v[0:1], 0, v[2:3]
	v_lshlrev_b64 v[0:1], 13, v[12:13]
	v_lshl_add_u64 v[28:29], v[14:15], 0, v[0:1]
	s_mov_b32 s12, 0x40000
	v_add_co_u32_e32 v16, vcc, s12, v28
	s_mov_b32 s12, 0x42000
	s_nop 0
	v_addc_co_u32_e32 v17, vcc, 0, v29, vcc
	v_or_b32_e32 v4, 1, v12
	v_or_b32_e32 v8, 2, v12
	v_or_b32_e32 v12, 3, v12
	v_add_co_u32_e32 v20, vcc, s12, v28
	v_ashrrev_i32_e32 v5, 31, v4
	v_ashrrev_i32_e32 v9, 31, v8
	v_ashrrev_i32_e32 v13, 31, v12
	v_addc_co_u32_e32 v21, vcc, 0, v29, vcc
	s_mov_b32 s12, 0x44000
	v_lshlrev_b64 v[4:5], 13, v[4:5]
	v_lshlrev_b64 v[8:9], 13, v[8:9]
	v_lshlrev_b64 v[12:13], 13, v[12:13]
	v_add_co_u32_e32 v24, vcc, s12, v28
	v_lshl_add_u64 v[4:5], v[14:15], 0, v[4:5]
	v_lshl_add_u64 v[8:9], v[14:15], 0, v[8:9]
	v_lshl_add_u64 v[12:13], v[14:15], 0, v[12:13]
	v_addc_co_u32_e32 v25, vcc, 0, v29, vcc
	s_mov_b32 s12, 0x46000
	flat_load_dwordx4 v[0:3], v[28:29]
	v_add_co_u32_e32 v28, vcc, s12, v28
	flat_load_dwordx4 v[4:7], v[4:5]
	s_nop 0
	v_addc_co_u32_e32 v29, vcc, 0, v29, vcc
	flat_load_dwordx4 v[8:11], v[8:9]
	s_lshl_b32 s12, s40, 1
	flat_load_dwordx4 v[12:15], v[12:13]
	s_add_u32 s14, s14, s12
	flat_load_dwordx4 v[16:19], v[16:17]
	s_addc_u32 s15, s15, 0
	flat_load_dwordx4 v[20:23], v[20:21]
	flat_load_dwordx4 v[24:27], v[24:25]
	flat_load_dwordx4 v[28:31], v[28:29]
	s_waitcnt vmcnt(0) lgkmcnt(0)
	v_cvt_pk_bf16_f32 v32, v0, v4
	v_add_u32_e32 v4, v41, v37
	v_cvt_pk_bf16_f32 v0, v1, v5
	v_cvt_pk_bf16_f32 v33, v8, v12
	v_cvt_pk_bf16_f32 v1, v9, v13
	ds_write2_b64 v4, v[32:33], v[0:1] offset1:16
	v_cvt_pk_bf16_f32 v0, v2, v6
	v_cvt_pk_bf16_f32 v1, v10, v14
	v_cvt_pk_bf16_f32 v2, v3, v7
	v_cvt_pk_bf16_f32 v3, v11, v15
	ds_write2_b64 v4, v[0:1], v[2:3] offset0:32 offset1:48
	v_cvt_pk_bf16_f32 v0, v16, v20
	v_add_u32_e32 v4, v44, v37
	v_cvt_pk_bf16_f32 v2, v17, v21
	s_waitcnt vmcnt(0) lgkmcnt(0)
	v_cvt_pk_bf16_f32 v1, v24, v28
	v_cvt_pk_bf16_f32 v3, v25, v29
	ds_write2_b64 v4, v[0:1], v[2:3] offset1:16
	v_cvt_pk_bf16_f32 v0, v18, v22
	v_cvt_pk_bf16_f32 v1, v26, v30
	v_cvt_pk_bf16_f32 v2, v19, v23
	v_cvt_pk_bf16_f32 v3, v27, v31
	ds_write2_b64 v4, v[0:1], v[2:3] offset0:32 offset1:48
	v_add_u32_e32 v0, v46, v47
	s_waitcnt lgkmcnt(0)
	s_barrier
	ds_read_b128 v[2:5], v0
	v_add_u32_e32 v0, s19, v45
	v_ashrrev_i32_e32 v1, 31, v0
	v_lshlrev_b64 v[0:1], 14, v[0:1]
	v_lshl_add_u64 v[6:7], s[14:15], 0, v[0:1]
	v_lshlrev_b32_e32 v0, 1, v40
	v_mov_b32_e32 v1, v96
	v_lshl_add_u64 v[6:7], v[6:7], 0, v[0:1]
	s_waitcnt lgkmcnt(0)
	flat_store_dwordx4 v[6:7], v[2:5]
	v_add_u32_e32 v6, s19, v48
	v_ashrrev_i32_e32 v7, 31, v6
	v_add_u32_e32 v2, v49, v47
	ds_read_b128 v[2:5], v2
	v_lshlrev_b64 v[6:7], 14, v[6:7]
	v_lshl_add_u64 v[6:7], s[14:15], 0, v[6:7]
	v_lshl_add_u64 v[6:7], v[6:7], 0, v[0:1]
	s_waitcnt lgkmcnt(0)
	flat_store_dwordx4 v[6:7], v[2:5]
	v_add_u32_e32 v6, s19, v50
	s_nop 0
	v_add_u32_e32 v2, v51, v47
	ds_read_b128 v[2:5], v2
	v_ashrrev_i32_e32 v7, 31, v6
	v_lshlrev_b64 v[6:7], 14, v[6:7]
	v_lshl_add_u64 v[6:7], s[14:15], 0, v[6:7]
	v_lshl_add_u64 v[6:7], v[6:7], 0, v[0:1]
	s_waitcnt lgkmcnt(0)
	flat_store_dwordx4 v[6:7], v[2:5]
	v_add_u32_e32 v6, s19, v52
	v_ashrrev_i32_e32 v7, 31, v6
	v_add_u32_e32 v2, v53, v47
	ds_read_b128 v[2:5], v2
	v_lshlrev_b64 v[6:7], 14, v[6:7]
	v_lshl_add_u64 v[6:7], s[14:15], 0, v[6:7]
	v_lshl_add_u64 v[0:1], v[6:7], 0, v[0:1]
	s_mov_b64 s[14:15], 0
	s_waitcnt lgkmcnt(0)
	flat_store_dwordx4 v[0:1], v[2:5]
	s_waitcnt lgkmcnt(0)
	s_barrier
.LBB0_641:
	s_andn2_b64 vcc, exec, s[14:15]
	s_cbranch_vccnz .LBB0_661
	v_mov_b64_e32 v[0:1], s[44:45]
	v_mov_b32_e32 v4, v64
	v_mov_b32_e32 v5, v65
	v_mov_b32_e32 v6, v66
	v_mov_b32_e32 v7, v67
	s_ashr_i32 s12, s18, 31
	s_lshr_b32 s12, s12, 22
	s_add_i32 s12, s18, s12
	s_ashr_i32 s13, s12, 10
	s_add_i32 s26, s13, s9
	s_and_b32 s12, s12, 0xfc00
	s_sub_i32 s14, s18, s12
	s_lshl_b64 s[12:13], s[26:27], 26
	v_mov_b32_e32 v3, v96
	s_nop 0
	v_lshl_add_u64 v[0:1], v[6:7], 0, s[12:13]
	s_sext_i32_i16 s12, s14
	s_bfe_u32 s12, s12, 0x5001a
	s_add_i32 s12, s14, s12
	s_sext_i32_i16 s13, s12
	s_and_b32 s12, s12, 0xffe0
	s_sub_i32 s12, s14, s12
	s_sext_i32_i16 s12, s12
	s_lshl_b32 s14, s12, 8
	v_or_b32_e32 v2, s14, v36
	s_ashr_i32 s15, s14, 31
	s_lshl_b32 s13, s13, 1
	v_cmp_gt_i32_e64 s[40:41], s3, v2
	v_lshl_add_u64 v[0:1], s[14:15], 2, v[0:1]
	v_lshlrev_b32_e32 v2, 2, v36
	s_and_b32 s50, s13, 0xffffffc0
	v_lshl_add_u64 v[42:43], v[0:1], 0, v[2:3]
	v_mov_b32_e32 v2, v96
	v_add_u32_e32 v34, s50, v38
	v_mov_b32_e32 v0, v96
	v_mov_b32_e32 v1, v96
	v_mov_b64_e32 v[8:9], v[2:3]
	v_ashrrev_i32_e32 v35, 31, v34
	v_mov_b64_e32 v[6:7], v[0:1]
	s_and_saveexec_b64 s[18:19], s[40:41]
	s_cbranch_execz .LBB0_644
	v_lshlrev_b64 v[6:7], 15, v[34:35]
	v_lshl_add_u64 v[6:7], v[42:43], 0, v[6:7]
	flat_load_dwordx4 v[6:9], v[6:7]

; #define LAS __attribute__((address_space(3)))
; __device__ __forceinline__ void transpose_item(Frame& F, const float* W, int K, int N, bf16* WT, int kb, int nb, const float* gk = nullptr) {
;     const int l = F.tid & 63, kg = F.tid >> 6, k0 = kb * 64, n0 = nb * 256;
;     const bool inb = (n0 + 4 * l) < N;
;     f32x4 v[2][4];
; #pragma unroll
;     for (int rep = 0; rep < 2; ++rep)
; #pragma unroll
;         for (int kk = 0; kk < 4; ++kk) v[rep][kk] = inb ? *(const f32x4*)(W + (size_t)(k0 + 4 * (kg + 8 * rep) + kk) * N + n0 + 4 * l) : (f32x4){0.f, 0.f, 0.f, 0.f};
;     if (gk) {
; #pragma unroll
;         for (int rep = 0; rep < 2; ++rep) { const f32x4 gg = *(const f32x4*)(gk + k0 + 4 * (kg + 8 * rep)); v[rep][0] = v[rep][0] * gg.x; v[rep][1] = v[rep][1] * gg.y; v[rep][2] = v[rep][2] * gg.z; v[rep][3] = v[rep][3] * gg.w; } }
; #pragma unroll
;     for (int rep = 0; rep < 2; ++rep) { const int kq = kg + 8 * rep;
; #pragma unroll
;         for (int i = 0; i < 4; ++i) { const int n = 4 * l + i; v2u w; w.x = pk2(v[rep][0][i], v[rep][1][i]); w.y = pk2(v[rep][2][i], v[rep][3][i]);
;             *(LAS v2u*)(F.lds + n * 128 + (((kq >> 1) ^ (l & 7)) * 16) + (kq & 1) * 8) = w; } }
;     __syncthreads();
; #pragma unroll
;     for (int q = 0; q < 4; ++q) { const int p = F.tid + 512 * q, n = p >> 3, j = p & 7;
;         const v4u d = *(const LAS v4u*)(F.lds + n * 128 + ((j ^ ((n >> 2) & 7)) * 16));
;         *(v4u*)(WT + (size_t)(n0 + n) * K + k0 + 8 * j) = d; }
;     __syncthreads();
; __device__ __forceinline__ void convert_weights(Frame& F, const int part, const int first, const int stride) {
;     ...
;         if (r < n_out) { const int l = l0 + r / I_OUT; r %= I_OUT; transpose_item(F, F.in[11] + (size_t)l * D * D, D, D, wout + (size_t)l * D * D, r / 8, r % 8); continue; } r -= n_out;
.LBB0_662:
	s_andn2_b64 vcc, exec, s[14:15]
	s_cbranch_vccnz .LBB0_664
	v_mov_b64_e32 v[0:1], s[44:45]
	v_mov_b32_e32 v0, v68
	v_mov_b32_e32 v1, v69
	s_lshr_b32 s12, s92, 8
	s_add_i32 s26, s12, s9
	s_lshl_b64 s[12:13], s[26:27], 24
	v_lshlrev_b32_e32 v2, 2, v36
	v_mov_b32_e32 v3, v96
	s_nop 0
	v_lshl_add_u64 v[0:1], v[0:1], 0, s[12:13]
	s_lshl_b64 s[12:13], s[26:27], 23
	s_add_u32 s14, s53, s12
	s_addc_u32 s15, s57, s13
	s_add_i32 s12, s73, 0xfffff600
	s_and_b32 s19, s12, 0x7c0
	s_and_b32 s18, s67, 0x700
	v_add_u32_e32 v12, s19, v38
	s_lshl_b32 s26, s18, 2
	v_lshl_add_u64 v[0:1], v[0:1], 0, s[26:27]
	v_ashrrev_i32_e32 v13, 31, v12
	v_lshl_add_u64 v[14:15], v[0:1], 0, v[2:3]
	v_lshlrev_b64 v[0:1], 13, v[12:13]
	v_lshl_add_u64 v[28:29], v[14:15], 0, v[0:1]
	s_mov_b32 s12, 0x40000
	v_add_co_u32_e32 v16, vcc, s12, v28
	s_mov_b32 s12, 0x42000
	s_nop 0
	v_addc_co_u32_e32 v17, vcc, 0, v29, vcc
	v_or_b32_e32 v4, 1, v12
	v_or_b32_e32 v8, 2, v12
	v_or_b32_e32 v12, 3, v12
	v_add_co_u32_e32 v20, vcc, s12, v28
	v_ashrrev_i32_e32 v5, 31, v4
	v_ashrrev_i32_e32 v9, 31, v8
	v_ashrrev_i32_e32 v13, 31, v12
	v_addc_co_u32_e32 v21, vcc, 0, v29, vcc
	s_mov_b32 s12, 0x44000
	v_lshlrev_b64 v[4:5], 13, v[4:5]
	v_lshlrev_b64 v[8:9], 13, v[8:9]
	v_lshlrev_b64 v[12:13], 13, v[12:13]
	v_add_co_u32_e32 v24, vcc, s12, v28
	v_lshl_add_u64 v[4:5], v[14:15], 0, v[4:5]
	v_lshl_add_u64 v[8:9], v[14:15], 0, v[8:9]
	v_lshl_add_u64 v[12:13], v[14:15], 0, v[12:13]
	v_addc_co_u32_e32 v25, vcc, 0, v29, vcc
	s_mov_b32 s12, 0x46000
	flat_load_dwordx4 v[0:3], v[28:29]
	v_add_co_u32_e32 v28, vcc, s12, v28
	flat_load_dwordx4 v[4:7], v[4:5]
	s_nop 0
	v_addc_co_u32_e32 v29, vcc, 0, v29, vcc
	flat_load_dwordx4 v[8:11], v[8:9]
	s_lshl_b32 s12, s19, 1
	flat_load_dwordx4 v[12:15], v[12:13]
	s_add_u32 s14, s14, s12
	flat_load_dwordx4 v[16:19], v[16:17]
	s_addc_u32 s15, s15, 0
	flat_load_dwordx4 v[20:23], v[20:21]
	flat_load_dwordx4 v[24:27], v[24:25]
	flat_load_dwordx4 v[28:31], v[28:29]
	s_waitcnt vmcnt(0) lgkmcnt(0)
	v_cvt_pk_bf16_f32 v32, v0, v4
	v_add_u32_e32 v4, v41, v37
	v_cvt_pk_bf16_f32 v0, v1, v5
	v_cvt_pk_bf16_f32 v33, v8, v12
	v_cvt_pk_bf16_f32 v1, v9, v13
	ds_write2_b64 v4, v[32:33], v[0:1] offset1:16
	v_cvt_pk_bf16_f32 v0, v2, v6
	v_cvt_pk_bf16_f32 v1, v10, v14
	v_cvt_pk_bf16_f32 v2, v3, v7
	v_cvt_pk_bf16_f32 v3, v11, v15
	ds_write2_b64 v4, v[0:1], v[2:3] offset0:32 offset1:48
	v_cvt_pk_bf16_f32 v0, v16, v20
	v_add_u32_e32 v4, v44, v37
	v_cvt_pk_bf16_f32 v2, v17, v21
	s_waitcnt vmcnt(0) lgkmcnt(0)
	v_cvt_pk_bf16_f32 v1, v24, v28
	v_cvt_pk_bf16_f32 v3, v25, v29
	ds_write2_b64 v4, v[0:1], v[2:3] offset1:16
	v_cvt_pk_bf16_f32 v0, v18, v22
	v_cvt_pk_bf16_f32 v1, v26, v30
	v_cvt_pk_bf16_f32 v2, v19, v23
	v_cvt_pk_bf16_f32 v3, v27, v31
	ds_write2_b64 v4, v[0:1], v[2:3] offset0:32 offset1:48
	v_add_u32_e32 v0, v46, v47
	s_waitcnt lgkmcnt(0)
	s_barrier
	ds_read_b128 v[2:5], v0
	v_add_u32_e32 v0, s18, v45
	v_ashrrev_i32_e32 v1, 31, v0
	v_lshlrev_b64 v[0:1], 12, v[0:1]
	v_lshl_add_u64 v[6:7], s[14:15], 0, v[0:1]
	v_lshlrev_b32_e32 v0, 1, v40
	v_mov_b32_e32 v1, v96
	v_lshl_add_u64 v[6:7], v[6:7], 0, v[0:1]
	s_waitcnt lgkmcnt(0)
	flat_store_dwordx4 v[6:7], v[2:5]
	v_add_u32_e32 v6, s18, v48
	v_ashrrev_i32_e32 v7, 31, v6
	v_add_u32_e32 v2, v49, v47
	ds_read_b128 v[2:5], v2
	v_lshlrev_b64 v[6:7], 12, v[6:7]
	v_lshl_add_u64 v[6:7], s[14:15], 0, v[6:7]
	v_lshl_add_u64 v[6:7], v[6:7], 0, v[0:1]
	s_waitcnt lgkmcnt(0)
	flat_store_dwordx4 v[6:7], v[2:5]
	v_add_u32_e32 v6, s18, v50
	s_nop 0
	v_add_u32_e32 v2, v51, v47
	ds_read_b128 v[2:5], v2
	v_ashrrev_i32_e32 v7, 31, v6
	v_lshlrev_b64 v[6:7], 12, v[6:7]
	v_lshl_add_u64 v[6:7], s[14:15], 0, v[6:7]
	v_lshl_add_u64 v[6:7], v[6:7], 0, v[0:1]
	s_waitcnt lgkmcnt(0)
	flat_store_dwordx4 v[6:7], v[2:5]
	v_add_u32_e32 v6, s18, v52
	v_ashrrev_i32_e32 v7, 31, v6
	v_add_u32_e32 v2, v53, v47
	ds_read_b128 v[2:5], v2
	v_lshlrev_b64 v[6:7], 12, v[6:7]
	v_lshl_add_u64 v[6:7], s[14:15], 0, v[6:7]
	v_lshl_add_u64 v[0:1], v[6:7], 0, v[0:1]
	s_waitcnt lgkmcnt(0)
	flat_store_dwordx4 v[0:1], v[2:5]
	s_waitcnt lgkmcnt(0)
	s_barrier

; __device__ __forceinline__ void transpose_item(Frame& F, const float* W, int K, int N, bf16* WT, int kb, int nb, const float* gk = nullptr) {
;     const int l = F.tid & 63, kg = F.tid >> 6, k0 = kb * 64, n0 = nb * 256;
;     const bool inb = (n0 + 4 * l) < N;
;     f32x4 v[2][4];
; #pragma unroll
;     for (int rep = 0; rep < 2; ++rep)
; #pragma unroll
;         for (int kk = 0; kk < 4; ++kk) v[rep][kk] = inb ? *(const f32x4*)(W + (size_t)(k0 + 4 * (kg + 8 * rep) + kk) * N + n0 + 4 * l) : (f32x4){0.f, 0.f, 0.f, 0.f};
; __device__ __forceinline__ void convert_weights(Frame& F, const int part, const int first, const int stride) {
;     ...
;         if (r < n_swa) { const int l = part - 1; transpose_item(F, F.in[8] + (size_t)l * D * SWA_IN, D, SWA_IN, wswa + (size_t)l * SWA_NP * D, r / 10, r % 10, F.in[3] + (2 * l + 1) * D); continue; } r -= n_swa;
.LBB0_665:
	s_andn2_b64 vcc, exec, s[14:15]
	s_cbranch_vccnz .LBB0_685
	v_mov_b64_e32 v[0:1], s[44:45]
	v_mov_b32_e32 v4, v70
	v_mov_b32_e32 v5, v71
	v_mov_b32_e32 v32, v72
	v_mov_b32_e32 v33, v73
	s_mul_hi_i32 s12, s85, 0x66666667
	s_lshr_b32 s13, s12, 31
	s_ashr_i32 s12, s12, 2
	s_add_i32 s12, s12, s13
	s_mul_i32 s13, s12, 10
	s_lshl_b32 s40, s12, 6
	s_sub_i32 s12, s85, s13
	s_lshl_b32 s14, s12, 8
	s_ashr_i32 s15, s14, 31
	v_lshlrev_b32_e32 v6, 2, v36
	v_mov_b32_e32 v7, v96
	v_mov_b32_e32 v2, v96
	v_mov_b32_e32 v3, v96
	v_mov_b32_e32 v0, v96
	v_mov_b32_e32 v1, v96
	v_or_b32_e32 v8, s14, v36
	s_movk_i32 s12, 0x980
	v_add_u32_e32 v42, s40, v38
	v_cmp_gt_i32_e32 vcc, s12, v8
	s_nop 0
	v_lshl_add_u64 v[4:5], v[4:5], 0, s[0:1]
	v_lshl_add_u64 v[4:5], s[14:15], 2, v[4:5]
	v_lshl_add_u64 v[34:35], v[4:5], 0, v[6:7]
	v_mov_b64_e32 v[6:7], v[2:3]
	v_mov_b64_e32 v[4:5], v[0:1]
	s_and_saveexec_b64 s[18:19], vcc
	s_cbranch_execz .LBB0_668
	s_movk_i32 s12, 0x2600
	v_mad_i64_i32 v[4:5], s[12:13], v42, s12, v[34:35]
	flat_load_dwordx4 v[4:7], v[4:5]

; __device__ __forceinline__ void transpose_item(Frame& F, const float* W, int K, int N, bf16* WT, int kb, int nb, const float* gk = nullptr) {
;     const int l = F.tid & 63, kg = F.tid >> 6, k0 = kb * 64, n0 = nb * 256;
;     const bool inb = (n0 + 4 * l) < N;
;     f32x4 v[2][4];
; #pragma unroll
;     for (int rep = 0; rep < 2; ++rep)
; #pragma unroll
;         for (int kk = 0; kk < 4; ++kk) v[rep][kk] = inb ? *(const f32x4*)(W + (size_t)(k0 + 4 * (kg + 8 * rep) + kk) * N + n0 + 4 * l) : (f32x4){0.f, 0.f, 0.f, 0.f};
; __device__ __forceinline__ void convert_weights(Frame& F, const int part, const int first, const int stride) {
;     ...
;         if (r < n_gla) { const int l = part; transpose_item(F, F.in[4] + (size_t)l * D * GLA_IN, D, GLA_IN, wgla + (size_t)l * GLA_NP * D, r / 23, r % 23, F.in[3] + (2 * l) * D); continue; } r -= n_gla;
.LBB0_686:
	s_andn2_b64 vcc, exec, s[14:15]
	s_cbranch_vccnz .LBB0_635
	v_mov_b64_e32 v[0:1], s[44:45]
	v_mov_b32_e32 v32, v72
	v_mov_b32_e32 v33, v73
	v_mov_b32_e32 v34, v74
	v_mov_b32_e32 v35, v75
	s_mul_hi_i32 s12, s8, 0xb21642c9
	s_add_i32 s12, s12, s8
	s_lshr_b32 s13, s12, 31
	s_ashr_i32 s12, s12, 4
	s_add_i32 s12, s12, s13
	s_lshl_b32 s40, s12, 6
	s_mulk_i32 s12, 0xe900
	s_add_i32 s14, s67, s12
	v_add_u32_e32 v6, s14, v36
	s_movk_i32 s12, 0x1610
	s_ashr_i32 s15, s14, 31
	v_cmp_gt_i32_e32 vcc, s12, v6
	v_lshlrev_b32_e32 v4, 2, v36
	v_mov_b32_e32 v5, v96
	v_mov_b32_e32 v2, v96
	v_mov_b32_e32 v3, v96
	v_mov_b32_e32 v0, v96
	v_mov_b32_e32 v1, v96
	v_add_u32_e32 v42, s40, v38
	s_nop 0
	v_lshl_add_u64 v[6:7], v[34:35], 0, s[46:47]
	v_lshl_add_u64 v[6:7], s[14:15], 2, v[6:7]
	v_lshl_add_u64 v[34:35], v[6:7], 0, v[4:5]
	v_mov_b64_e32 v[6:7], v[2:3]
	v_mov_b64_e32 v[4:5], v[0:1]
	s_and_saveexec_b64 s[18:19], vcc
	s_cbranch_execz .LBB0_689
	s_movk_i32 s12, 0x5840
	v_mad_i64_i32 v[4:5], s[12:13], v42, s12, v[34:35]
	flat_load_dwordx4 v[4:7], v[4:5]
